# v29 + LN row loop: nt hint on the once-read x / out-projection loads and the residual X stores
# speedup vs baseline: 1.0041x; 1.0041x over previous
; __device__ __forceinline__ void phase_ln(const Params& P, int l) {
;     ...
;     for (int row = bx * 8 + wid; row < T; row += G * 8) {
;         f32x4 v[8];
; #pragma unroll
;         for (int i = 0; i < 8; ++i) v[i] = *(const f32x4*)(xsrc + (size_t)row * 2048 + (i * 64 + lane) * 4);
;         if (l >= 1) {
;             const float* gp = gate + (size_t)(row >> 11) * 6144;
; #pragma unroll
;             for (int i = 0; i < 8; ++i) { const int col = (i * 64 + lane) * 4; const u32x2 ow = *(const u32x2*)(outb + (size_t)row * 2048 + col); const f32x4 gv = *(const f32x4*)(gp + col);
;                 f32x4 o; o[0] = __uint_as_float(ow.x << 16); o[1] = __uint_as_float(ow.x & 0xffff0000u); o[2] = __uint_as_float(ow.y << 16); o[3] = __uint_as_float(ow.y & 0xffff0000u);
;                 v[i] = v[i] * ALPHA + gv * o; }
.Lln_row:
	s_mul_i32 s9, s16, 0x18000
	s_add_u32 s9, s9, 0x15a04100
	s_lshl_b32 s10, s13, 13
	s_add_u32 s22, s4, s10
	s_addc_u32 s23, s5, 0
	global_load_dwordx4 v[16:19], v0, s[22:23] offset:0 nt
	global_load_dwordx4 v[20:23], v0, s[22:23] offset:1024 nt
	global_load_dwordx4 v[24:27], v0, s[22:23] offset:2048 nt
	global_load_dwordx4 v[28:31], v0, s[22:23] offset:3072 nt
	global_load_dwordx4 v[32:35], v2, s[22:23] offset:0 nt
	global_load_dwordx4 v[36:39], v2, s[22:23] offset:1024 nt
	global_load_dwordx4 v[40:43], v2, s[22:23] offset:2048 nt
	global_load_dwordx4 v[44:47], v2, s[22:23] offset:3072 nt
	s_cmp_eq_u32 s16, 0
	s_cbranch_scc1 .Lln_nold1
	s_lshl_b32 s11, s13, 12
	s_add_u32 s11, s11, 0x1bc64100
	s_add_u32 s24, s88, s11
	s_addc_u32 s25, s89, 0
	global_load_dwordx2 v[144:145], v3, s[24:25] offset:0 nt
	global_load_dwordx2 v[146:147], v3, s[24:25] offset:512 nt
	global_load_dwordx2 v[148:149], v3, s[24:25] offset:1024 nt
	global_load_dwordx2 v[150:151], v3, s[24:25] offset:1536 nt
	global_load_dwordx2 v[152:153], v3, s[24:25] offset:2048 nt
	global_load_dwordx2 v[154:155], v3, s[24:25] offset:2560 nt
	global_load_dwordx2 v[156:157], v3, s[24:25] offset:3072 nt
	global_load_dwordx2 v[158:159], v3, s[24:25] offset:3584 nt
	s_lshr_b32 s11, s13, 11
	s_mul_i32 s11, s11, 0x6000
	s_add_u32 s11, s11, s8
	s_add_u32 s26, s88, s11
	s_addc_u32 s27, s89, 0
	global_load_dwordx4 v[112:115], v0, s[26:27] offset:0
	global_load_dwordx4 v[116:119], v0, s[26:27] offset:1024
	global_load_dwordx4 v[120:123], v0, s[26:27] offset:2048
	global_load_dwordx4 v[124:127], v0, s[26:27] offset:3072
	global_load_dwordx4 v[128:131], v2, s[26:27] offset:0
	global_load_dwordx4 v[132:135], v2, s[26:27] offset:1024
	global_load_dwordx4 v[136:139], v2, s[26:27] offset:2048
	global_load_dwordx4 v[140:143], v2, s[26:27] offset:3072
	s_waitcnt vmcnt(0)
	v_lshlrev_b32_e32 v224, 16, v144
	v_and_b32_e32 v225, 0xffff0000, v144
	v_lshlrev_b32_e32 v226, 16, v145
	v_and_b32_e32 v227, 0xffff0000, v145
	v_pk_mul_f32 v[224:225], v[112:113], v[224:225]
	v_pk_mul_f32 v[226:227], v[114:115], v[226:227]
	v_fma_f32 v16, v16, s17, v224
	v_fma_f32 v17, v17, s17, v225
	v_fma_f32 v18, v18, s17, v226
	v_fma_f32 v19, v19, s17, v227
	v_lshlrev_b32_e32 v224, 16, v146
	v_and_b32_e32 v225, 0xffff0000, v146
	v_lshlrev_b32_e32 v226, 16, v147
	v_and_b32_e32 v227, 0xffff0000, v147
	v_pk_mul_f32 v[224:225], v[116:117], v[224:225]
	v_pk_mul_f32 v[226:227], v[118:119], v[226:227]
	v_fma_f32 v20, v20, s17, v224
	v_fma_f32 v21, v21, s17, v225
	v_fma_f32 v22, v22, s17, v226
	v_fma_f32 v23, v23, s17, v227
	v_lshlrev_b32_e32 v224, 16, v148
	v_and_b32_e32 v225, 0xffff0000, v148
	v_lshlrev_b32_e32 v226, 16, v149
	v_and_b32_e32 v227, 0xffff0000, v149
	v_pk_mul_f32 v[224:225], v[120:121], v[224:225]
	v_pk_mul_f32 v[226:227], v[122:123], v[226:227]
	v_fma_f32 v24, v24, s17, v224
	v_fma_f32 v25, v25, s17, v225
	v_fma_f32 v26, v26, s17, v226
	v_fma_f32 v27, v27, s17, v227
	v_lshlrev_b32_e32 v224, 16, v150
	v_and_b32_e32 v225, 0xffff0000, v150
	v_lshlrev_b32_e32 v226, 16, v151
	v_and_b32_e32 v227, 0xffff0000, v151
	v_pk_mul_f32 v[224:225], v[124:125], v[224:225]
	v_pk_mul_f32 v[226:227], v[126:127], v[226:227]
	v_fma_f32 v28, v28, s17, v224
	v_fma_f32 v29, v29, s17, v225
	v_fma_f32 v30, v30, s17, v226
	v_fma_f32 v31, v31, s17, v227
	v_lshlrev_b32_e32 v224, 16, v152
	v_and_b32_e32 v225, 0xffff0000, v152
	v_lshlrev_b32_e32 v226, 16, v153
	v_and_b32_e32 v227, 0xffff0000, v153
	v_pk_mul_f32 v[224:225], v[128:129], v[224:225]
	v_pk_mul_f32 v[226:227], v[130:131], v[226:227]
	v_fma_f32 v32, v32, s17, v224
	v_fma_f32 v33, v33, s17, v225
	v_fma_f32 v34, v34, s17, v226
	v_fma_f32 v35, v35, s17, v227
	v_lshlrev_b32_e32 v224, 16, v154
	v_and_b32_e32 v225, 0xffff0000, v154
	v_lshlrev_b32_e32 v226, 16, v155
	v_and_b32_e32 v227, 0xffff0000, v155
	v_pk_mul_f32 v[224:225], v[132:133], v[224:225]
	v_pk_mul_f32 v[226:227], v[134:135], v[226:227]
	v_fma_f32 v36, v36, s17, v224
	v_fma_f32 v37, v37, s17, v225
	v_fma_f32 v38, v38, s17, v226
	v_fma_f32 v39, v39, s17, v227
	v_lshlrev_b32_e32 v224, 16, v156
	v_and_b32_e32 v225, 0xffff0000, v156
	v_lshlrev_b32_e32 v226, 16, v157
	v_and_b32_e32 v227, 0xffff0000, v157
	v_pk_mul_f32 v[224:225], v[136:137], v[224:225]
	v_pk_mul_f32 v[226:227], v[138:139], v[226:227]
	v_fma_f32 v40, v40, s17, v224
	v_fma_f32 v41, v41, s17, v225
	v_fma_f32 v42, v42, s17, v226
	v_fma_f32 v43, v43, s17, v227
	v_lshlrev_b32_e32 v224, 16, v158
	v_and_b32_e32 v225, 0xffff0000, v158
	v_lshlrev_b32_e32 v226, 16, v159
	v_and_b32_e32 v227, 0xffff0000, v159
	v_pk_mul_f32 v[224:225], v[140:141], v[224:225]
	v_pk_mul_f32 v[226:227], v[142:143], v[226:227]
	v_fma_f32 v44, v44, s17, v224
	v_fma_f32 v45, v45, s17, v225
	v_fma_f32 v46, v46, s17, v226
	v_fma_f32 v47, v47, s17, v227
; __device__ __forceinline__ void row_stats(const f32x4 (&v)[8], float& mean, float& rstd) {
;     float s = 0.f;
; #pragma unroll
;     for (int i = 0; i < 8; ++i) s += (v[i][0] + v[i][1]) + (v[i][2] + v[i][3]);
;     mean = wave_sum(s) * (1.f / 2048.f);
;     float q = 0.f;
; #pragma unroll
;     for (int i = 0; i < 8; ++i) { const f32x4 d = v[i] - mean; q += (d[0] * d[0] + d[1] * d[1]) + (d[2] * d[2] + d[3] * d[3]); }
;     rstd = rsqrtf(wave_sum(q) * (1.f / 2048.f) + 1e-5f);
; __device__ __forceinline__ void phase_ln(const Params& P, int l) {
;     ...
;         const float* mp = mod + (size_t)(row >> 11) * 6144;
; #pragma unroll
;         for (int i = 0; i < 8; ++i) { const int col = (i * 64 + lane) * 4; const f32x4 sh = *(const f32x4*)(mp + col), sc = *(const f32x4*)(mp + 2048 + col);
.Lln_nold1:
	s_lshr_b32 s11, s13, 11
	s_mul_i32 s11, s11, 0x6000
	s_add_u32 s11, s11, s9
	s_add_u32 s26, s88, s11
	s_addc_u32 s27, s89, 0
	global_load_dwordx4 v[112:115], v0, s[26:27] offset:0
	global_load_dwordx4 v[116:119], v0, s[26:27] offset:1024
	global_load_dwordx4 v[120:123], v0, s[26:27] offset:2048
	global_load_dwordx4 v[124:127], v0, s[26:27] offset:3072
	global_load_dwordx4 v[128:131], v2, s[26:27] offset:0
	global_load_dwordx4 v[132:135], v2, s[26:27] offset:1024
	global_load_dwordx4 v[136:139], v2, s[26:27] offset:2048
	global_load_dwordx4 v[140:143], v2, s[26:27] offset:3072
	global_load_dwordx4 v[176:179], v10, s[26:27] offset:0
	global_load_dwordx4 v[180:183], v10, s[26:27] offset:1024
	global_load_dwordx4 v[184:187], v10, s[26:27] offset:2048
	global_load_dwordx4 v[188:191], v10, s[26:27] offset:3072
	global_load_dwordx4 v[192:195], v11, s[26:27] offset:0
	global_load_dwordx4 v[196:199], v11, s[26:27] offset:1024
	global_load_dwordx4 v[200:203], v11, s[26:27] offset:2048
	global_load_dwordx4 v[204:207], v11, s[26:27] offset:3072
	s_cmp_eq_u32 s16, 0
	s_cbranch_scc1 .Lln_l0
	s_waitcnt vmcnt(16)
	v_pk_add_f32 v[224:225], v[16:17], v[18:19]
	v_pk_add_f32 v[224:225], v[224:225], v[20:21]
	v_pk_add_f32 v[224:225], v[224:225], v[22:23]
	v_pk_add_f32 v[224:225], v[224:225], v[24:25]
	v_pk_add_f32 v[224:225], v[224:225], v[26:27]
	v_pk_add_f32 v[224:225], v[224:225], v[28:29]
	v_pk_add_f32 v[224:225], v[224:225], v[30:31]
	v_pk_add_f32 v[224:225], v[224:225], v[32:33]
	v_pk_add_f32 v[224:225], v[224:225], v[34:35]
	v_pk_add_f32 v[224:225], v[224:225], v[36:37]
	v_pk_add_f32 v[224:225], v[224:225], v[38:39]
	v_pk_add_f32 v[224:225], v[224:225], v[40:41]
	v_pk_add_f32 v[224:225], v[224:225], v[42:43]
	v_pk_add_f32 v[224:225], v[224:225], v[44:45]
	v_pk_add_f32 v[224:225], v[224:225], v[46:47]
	v_add_f32_e32 v12, v224, v225
	ds_bpermute_b32 v13, v4, v12
	s_waitcnt lgkmcnt(0)
	v_add_f32_e32 v12, v12, v13
	ds_bpermute_b32 v13, v5, v12
	s_waitcnt lgkmcnt(0)
	v_add_f32_e32 v12, v12, v13
	ds_bpermute_b32 v13, v6, v12
	s_waitcnt lgkmcnt(0)
	v_add_f32_e32 v12, v12, v13
	ds_bpermute_b32 v13, v7, v12
	s_waitcnt lgkmcnt(0)
	v_add_f32_e32 v12, v12, v13
	ds_bpermute_b32 v13, v8, v12
	s_waitcnt lgkmcnt(0)
	v_add_f32_e32 v12, v12, v13
	ds_bpermute_b32 v13, v9, v12
	s_waitcnt lgkmcnt(0)
	v_add_f32_e32 v12, v12, v13
	v_mul_f32_e32 v14, 0x3a000000, v12
	v_pk_add_f32 v[226:227], v[16:17], v[14:15] op_sel_hi:[1,0] neg_lo:[0,1] neg_hi:[0,1]
	v_pk_mul_f32 v[224:225], v[226:227], v[226:227]
	v_pk_add_f32 v[226:227], v[18:19], v[14:15] op_sel_hi:[1,0] neg_lo:[0,1] neg_hi:[0,1]
	v_pk_fma_f32 v[224:225], v[226:227], v[226:227], v[224:225]
	v_pk_add_f32 v[226:227], v[20:21], v[14:15] op_sel_hi:[1,0] neg_lo:[0,1] neg_hi:[0,1]
	v_pk_fma_f32 v[224:225], v[226:227], v[226:227], v[224:225]
	v_pk_add_f32 v[226:227], v[22:23], v[14:15] op_sel_hi:[1,0] neg_lo:[0,1] neg_hi:[0,1]
	v_pk_fma_f32 v[224:225], v[226:227], v[226:227], v[224:225]
	v_pk_add_f32 v[226:227], v[24:25], v[14:15] op_sel_hi:[1,0] neg_lo:[0,1] neg_hi:[0,1]
	v_pk_fma_f32 v[224:225], v[226:227], v[226:227], v[224:225]
	v_pk_add_f32 v[226:227], v[26:27], v[14:15] op_sel_hi:[1,0] neg_lo:[0,1] neg_hi:[0,1]
	v_pk_fma_f32 v[224:225], v[226:227], v[226:227], v[224:225]
	v_pk_add_f32 v[226:227], v[28:29], v[14:15] op_sel_hi:[1,0] neg_lo:[0,1] neg_hi:[0,1]
	v_pk_fma_f32 v[224:225], v[226:227], v[226:227], v[224:225]
	v_pk_add_f32 v[226:227], v[30:31], v[14:15] op_sel_hi:[1,0] neg_lo:[0,1] neg_hi:[0,1]
	v_pk_fma_f32 v[224:225], v[226:227], v[226:227], v[224:225]
	v_pk_add_f32 v[226:227], v[32:33], v[14:15] op_sel_hi:[1,0] neg_lo:[0,1] neg_hi:[0,1]
	v_pk_fma_f32 v[224:225], v[226:227], v[226:227], v[224:225]
	v_pk_add_f32 v[226:227], v[34:35], v[14:15] op_sel_hi:[1,0] neg_lo:[0,1] neg_hi:[0,1]
	v_pk_fma_f32 v[224:225], v[226:227], v[226:227], v[224:225]
	v_pk_add_f32 v[226:227], v[36:37], v[14:15] op_sel_hi:[1,0] neg_lo:[0,1] neg_hi:[0,1]
	v_pk_fma_f32 v[224:225], v[226:227], v[226:227], v[224:225]
	v_pk_add_f32 v[226:227], v[38:39], v[14:15] op_sel_hi:[1,0] neg_lo:[0,1] neg_hi:[0,1]
	v_pk_fma_f32 v[224:225], v[226:227], v[226:227], v[224:225]
	v_pk_add_f32 v[226:227], v[40:41], v[14:15] op_sel_hi:[1,0] neg_lo:[0,1] neg_hi:[0,1]
	v_pk_fma_f32 v[224:225], v[226:227], v[226:227], v[224:225]
	v_pk_add_f32 v[226:227], v[42:43], v[14:15] op_sel_hi:[1,0] neg_lo:[0,1] neg_hi:[0,1]
	v_pk_fma_f32 v[224:225], v[226:227], v[226:227], v[224:225]
	v_pk_add_f32 v[226:227], v[44:45], v[14:15] op_sel_hi:[1,0] neg_lo:[0,1] neg_hi:[0,1]
	v_pk_fma_f32 v[224:225], v[226:227], v[226:227], v[224:225]
	v_pk_add_f32 v[226:227], v[46:47], v[14:15] op_sel_hi:[1,0] neg_lo:[0,1] neg_hi:[0,1]
	v_pk_fma_f32 v[224:225], v[226:227], v[226:227], v[224:225]
	v_add_f32_e32 v12, v224, v225
	ds_bpermute_b32 v13, v4, v12
	s_waitcnt lgkmcnt(0)
; __device__ __forceinline__ void row_stats(const f32x4 (&v)[8], float& mean, float& rstd) {
;     float s = 0.f;
; #pragma unroll
;     for (int i = 0; i < 8; ++i) s += (v[i][0] + v[i][1]) + (v[i][2] + v[i][3]);
;     mean = wave_sum(s) * (1.f / 2048.f);
;     float q = 0.f;
; #pragma unroll
;     for (int i = 0; i < 8; ++i) { const f32x4 d = v[i] - mean; q += (d[0] * d[0] + d[1] * d[1]) + (d[2] * d[2] + d[3] * d[3]); }
;     rstd = rsqrtf(wave_sum(q) * (1.f / 2048.f) + 1e-5f);
; __device__ __forceinline__ void phase_ln(const Params& P, int l) {
;     ...
;         if (l >= 1) {
;             float* dst = (l == 4) ? P.out : X;
; #pragma unroll
;             for (int i = 0; i < 8; ++i) { const int col = (i * 64 + lane) * 4; const f32x4 gv = *(const f32x4*)(g + col), bv = *(const f32x4*)(bb + col);
;                 v[i] = (v[i] - mean) * rstd * gv + bv; *(f32x4*)(dst + (size_t)row * 2048 + col) = v[i]; }
	v_add_f32_e32 v12, v12, v13
	ds_bpermute_b32 v13, v5, v12
	s_waitcnt lgkmcnt(0)
	v_add_f32_e32 v12, v12, v13
	ds_bpermute_b32 v13, v6, v12
	s_waitcnt lgkmcnt(0)
	v_add_f32_e32 v12, v12, v13
	ds_bpermute_b32 v13, v7, v12
	s_waitcnt lgkmcnt(0)
	v_add_f32_e32 v12, v12, v13
	ds_bpermute_b32 v13, v8, v12
	s_waitcnt lgkmcnt(0)
	v_add_f32_e32 v12, v12, v13
	ds_bpermute_b32 v13, v9, v12
	s_waitcnt lgkmcnt(0)
	v_add_f32_e32 v12, v12, v13
	v_mul_f32_e32 v12, 0x3a000000, v12
	v_add_f32_e32 v12, 0x3727c5ac, v12
	v_rsq_f32_e32 v12, v12
	s_nop 0
	v_pk_add_f32 v[226:227], v[16:17], v[14:15] op_sel_hi:[1,0] neg_lo:[0,1] neg_hi:[0,1]
	v_pk_mul_f32 v[226:227], v[226:227], v[12:13] op_sel_hi:[1,0]
	v_pk_fma_f32 v[16:17], v[226:227], v[48:49], v[80:81]
	v_pk_add_f32 v[226:227], v[18:19], v[14:15] op_sel_hi:[1,0] neg_lo:[0,1] neg_hi:[0,1]
	v_pk_mul_f32 v[226:227], v[226:227], v[12:13] op_sel_hi:[1,0]
	v_pk_fma_f32 v[18:19], v[226:227], v[50:51], v[82:83]
	v_pk_add_f32 v[226:227], v[20:21], v[14:15] op_sel_hi:[1,0] neg_lo:[0,1] neg_hi:[0,1]
	v_pk_mul_f32 v[226:227], v[226:227], v[12:13] op_sel_hi:[1,0]
	v_pk_fma_f32 v[20:21], v[226:227], v[52:53], v[84:85]
	v_pk_add_f32 v[226:227], v[22:23], v[14:15] op_sel_hi:[1,0] neg_lo:[0,1] neg_hi:[0,1]
	v_pk_mul_f32 v[226:227], v[226:227], v[12:13] op_sel_hi:[1,0]
	v_pk_fma_f32 v[22:23], v[226:227], v[54:55], v[86:87]
	v_pk_add_f32 v[226:227], v[24:25], v[14:15] op_sel_hi:[1,0] neg_lo:[0,1] neg_hi:[0,1]
	v_pk_mul_f32 v[226:227], v[226:227], v[12:13] op_sel_hi:[1,0]
	v_pk_fma_f32 v[24:25], v[226:227], v[56:57], v[88:89]
	v_pk_add_f32 v[226:227], v[26:27], v[14:15] op_sel_hi:[1,0] neg_lo:[0,1] neg_hi:[0,1]
	v_pk_mul_f32 v[226:227], v[226:227], v[12:13] op_sel_hi:[1,0]
	v_pk_fma_f32 v[26:27], v[226:227], v[58:59], v[90:91]
	v_pk_add_f32 v[226:227], v[28:29], v[14:15] op_sel_hi:[1,0] neg_lo:[0,1] neg_hi:[0,1]
	v_pk_mul_f32 v[226:227], v[226:227], v[12:13] op_sel_hi:[1,0]
	v_pk_fma_f32 v[28:29], v[226:227], v[60:61], v[92:93]
	v_pk_add_f32 v[226:227], v[30:31], v[14:15] op_sel_hi:[1,0] neg_lo:[0,1] neg_hi:[0,1]
	v_pk_mul_f32 v[226:227], v[226:227], v[12:13] op_sel_hi:[1,0]
	v_pk_fma_f32 v[30:31], v[226:227], v[62:63], v[94:95]
	v_pk_add_f32 v[226:227], v[32:33], v[14:15] op_sel_hi:[1,0] neg_lo:[0,1] neg_hi:[0,1]
	v_pk_mul_f32 v[226:227], v[226:227], v[12:13] op_sel_hi:[1,0]
	v_pk_fma_f32 v[32:33], v[226:227], v[64:65], v[96:97]
	v_pk_add_f32 v[226:227], v[34:35], v[14:15] op_sel_hi:[1,0] neg_lo:[0,1] neg_hi:[0,1]
	v_pk_mul_f32 v[226:227], v[226:227], v[12:13] op_sel_hi:[1,0]
	v_pk_fma_f32 v[34:35], v[226:227], v[66:67], v[98:99]
	v_pk_add_f32 v[226:227], v[36:37], v[14:15] op_sel_hi:[1,0] neg_lo:[0,1] neg_hi:[0,1]
	v_pk_mul_f32 v[226:227], v[226:227], v[12:13] op_sel_hi:[1,0]
	v_pk_fma_f32 v[36:37], v[226:227], v[68:69], v[100:101]
	v_pk_add_f32 v[226:227], v[38:39], v[14:15] op_sel_hi:[1,0] neg_lo:[0,1] neg_hi:[0,1]
	v_pk_mul_f32 v[226:227], v[226:227], v[12:13] op_sel_hi:[1,0]
	v_pk_fma_f32 v[38:39], v[226:227], v[70:71], v[102:103]
	v_pk_add_f32 v[226:227], v[40:41], v[14:15] op_sel_hi:[1,0] neg_lo:[0,1] neg_hi:[0,1]
	v_pk_mul_f32 v[226:227], v[226:227], v[12:13] op_sel_hi:[1,0]
	v_pk_fma_f32 v[40:41], v[226:227], v[72:73], v[104:105]
	v_pk_add_f32 v[226:227], v[42:43], v[14:15] op_sel_hi:[1,0] neg_lo:[0,1] neg_hi:[0,1]
	v_pk_mul_f32 v[226:227], v[226:227], v[12:13] op_sel_hi:[1,0]
	v_pk_fma_f32 v[42:43], v[226:227], v[74:75], v[106:107]
	v_pk_add_f32 v[226:227], v[44:45], v[14:15] op_sel_hi:[1,0] neg_lo:[0,1] neg_hi:[0,1]
	v_pk_mul_f32 v[226:227], v[226:227], v[12:13] op_sel_hi:[1,0]
	v_pk_fma_f32 v[44:45], v[226:227], v[76:77], v[108:109]
	v_pk_add_f32 v[226:227], v[46:47], v[14:15] op_sel_hi:[1,0] neg_lo:[0,1] neg_hi:[0,1]
	v_pk_mul_f32 v[226:227], v[226:227], v[12:13] op_sel_hi:[1,0]
	v_pk_fma_f32 v[46:47], v[226:227], v[78:79], v[110:111]
	s_lshl_b32 s10, s13, 13
	s_add_u32 s10, s10, 0x17c64100
	s_add_u32 s6, s88, s10
	s_addc_u32 s7, s89, 0
	global_store_dwordx4 v0, v[16:19], s[6:7] offset:0 nt
	global_store_dwordx4 v0, v[20:23], s[6:7] offset:1024 nt
	global_store_dwordx4 v0, v[24:27], s[6:7] offset:2048 nt
	global_store_dwordx4 v0, v[28:31], s[6:7] offset:3072 nt
	global_store_dwordx4 v2, v[32:35], s[6:7] offset:0 nt
	global_store_dwordx4 v2, v[36:39], s[6:7] offset:1024 nt
	global_store_dwordx4 v2, v[40:43], s[6:7] offset:2048 nt
	global_store_dwordx4 v2, v[44:47], s[6:7] offset:3072 nt
	s_branch .Lln_st2
